# grid barrier: leaders arrive on TOP with a non-returning add and all workgroups poll TOP >= (round+1)*nx (one memory round trip less per barrier), on top of v6
# speedup vs baseline: 1.0056x; 1.0056x over previous
.LBB0_966:
	v_readlane_b32 s2, v250, 49
	v_readlane_b32 s3, v250, 50
	v_mov_b32_e32 v5, 1
	v_cvt_f32_u32_e32 v6, v4
	v_sub_u32_e32 v7, 0, v4
	v_rcp_iflag_f32_e32 v6, v6
	s_nop 0
	global_atomic_add v5, v209, v5, s[2:3] sc0
	v_mul_f32_e32 v6, 0x4f7ffffe, v6
	v_cvt_u32_f32_e32 v6, v6
	v_mul_lo_u32 v7, v7, v6
	v_mul_hi_u32 v7, v6, v7
	v_add_u32_e32 v6, v6, v7
	s_waitcnt vmcnt(0)
	v_mul_hi_u32 v6, v5, v6
	v_mul_lo_u32 v7, v6, v4
	v_sub_u32_e32 v7, v5, v7
	v_cmp_ge_u32_e32 vcc, v7, v4
	v_add_u32_e32 v8, 1, v6
	v_add_u32_e32 v5, 1, v5
	v_cndmask_b32_e32 v6, v6, v8, vcc
	v_sub_u32_e32 v8, v7, v4
	v_cndmask_b32_e32 v7, v7, v8, vcc
	v_cmp_ge_u32_e32 vcc, v7, v4
	v_add_u32_e32 v7, 1, v6
	s_nop 0
	v_cndmask_b32_e32 v6, v6, v7, vcc
	v_mov_b32_e32 v7, s80
	ds_write_b32 v7, v6 offset:8
	v_mul_lo_u32 v6, v4, v6
	v_add_u32_e32 v4, v6, v4
	v_cmp_eq_u32_e32 vcc, v5, v4
	s_and_b64 exec, exec, vcc
	s_cbranch_execz .LBB0_972
	s_mov_b64 s[2:3], exec
	buffer_wbl2 sc1
	s_waitcnt lgkmcnt(0)
	s_waitcnt vmcnt(0)
	v_mbcnt_lo_u32_b32 v4, s2, 0
	v_mbcnt_hi_u32_b32 v4, s3, v4
	v_cmp_eq_u32_e32 vcc, 0, v4
	s_and_saveexec_b64 s[4:5], vcc
	s_cbranch_execz .LBB0_969
	s_bcnt1_i32_b64 s2, s[2:3]
	v_mov_b32_e32 v5, s2
	v_readlane_b32 s2, v250, 51
	v_readlane_b32 s3, v250, 52
	s_nop 4
	global_atomic_add v209, v5, s[2:3]
.LBB0_969:
	s_or_b64 exec, exec, s[4:5]
	s_branch .LBB0_972

.LBB0_1175:
	v_readlane_b32 s2, v250, 51
	v_mov_b32_e32 v0, s80
	v_readlane_b32 s3, v250, 52
	ds_read2_b32 v[2:3], v0 offset0:1 offset1:2
	s_nop 3
	global_load_dword v1, v209, s[2:3] sc1
	s_waitcnt lgkmcnt(0)
	v_mad_u32_u24 v0, v3, v2, v2
	s_waitcnt vmcnt(0)
	v_cmp_ge_u32_e32 vcc, v1, v0
	s_cbranch_vccz .LBB0_1176
	s_getpc_b64 s[98:99]

.LBB0_1180:
	v_readlane_b32 s2, v250, 51
	v_readlane_b32 s3, v250, 52
	s_add_i32 s8, s8, 1
	s_mov_b64 s[4:5], -1
	s_nop 2
	global_load_dword v1, v209, s[2:3] sc1
	s_waitcnt vmcnt(0)
	v_cmp_ge_u32_e64 s[2:3], v1, v0
	s_branch .LBB0_1177
